# fast path softmax row-sum with v_pk_add_f32 tree (8 instead of 16 adds per row set)
# speedup vs baseline: 1.0015x; 1.0015x over previous
; __device__ __forceinline__ unsigned cvt_pk_bf16(float lo, float hi) { unsigned r; asm volatile("v_cvt_pk_bf16_f32 %0, %1, %2" : "=v"(r) : "v"(lo), "v"(hi)); return r; }
; __device__ __forceinline__ f32x4 mfma16(bf16x8 a, bf16x8 b, f32x4 c) { return __builtin_amdgcn_mfma_f32_16x16x32_bf16(a, b, c, 0, 0, 0); }
; template <int MODE> __device__ __forceinline__ void tile_softmax(f32x4 (&S)[4], bool rowv, int kfirst, int klo, unsigned kspan, float& l) {
;     ...
;         for (int j = 0; j < 4; ++j) { float e = __builtin_amdgcn_exp2f(S[st][j]);
;             if (MODE == 1) e = rowv ? e : 0.f;
;             if (MODE == 2) e = ((unsigned)(kfirst + st * 16 + j - klo) <= kspan) ? e : 0.f;
;             S[st][j] = e; ps += e; }
;     l += ps;
; __device__ __forceinline__ void nsa_pack(const f32x4 (&P)[4], u32x4 (&pf)[2]) {
; #pragma unroll
;     for (int hf = 0; hf < 2; ++hf) { pf[hf].x = cvt_pk_bf16(P[2 * hf][0], P[2 * hf][1]); pf[hf].y = cvt_pk_bf16(P[2 * hf][2], P[2 * hf][3]); pf[hf].z = cvt_pk_bf16(P[2 * hf + 1][0], P[2 * hf + 1][1]); pf[hf].w = cvt_pk_bf16(P[2 * hf + 1][2], P[2 * hf + 1][3]); }
; }
; __device__ __forceinline__ void nsa_pv(const u32x4 (&vf)[2][4], const u32x4 (&pf)[2], f32x4 (&O)[4]) {
; #pragma unroll
;     for (int hf = 0; hf < 2; ++hf)
; #pragma unroll
;         for (int dt = 0; dt < 4; ++dt) O[dt] = mfma16(__builtin_bit_cast(bf16x8, vf[hf][dt]), __builtin_bit_cast(bf16x8, pf[hf]), O[dt]);
; }
.Lsel_fast_k:
	v_add_u32_e32 v126, s45, v197
	v_add_u32_e32 v127, s45, v198
	v_add_u32_e32 v128, s45, v199
	v_add_u32_e32 v129, s45, v206
	s_waitcnt lgkmcnt(0)
	s_and_b64 vcc, exec, s[56:57]
	s_cbranch_vccz .Lsf_only1
	s_and_b64 vcc, exec, s[28:29]
	s_cbranch_vccz .Lsf_only0
	v_mfma_f32_16x16x32_bf16 v[16:19], v[132:135], v[60:63], 0
	v_mfma_f32_16x16x32_bf16 v[20:23], v[136:139], v[60:63], 0
	v_mfma_f32_16x16x32_bf16 v[24:27], v[140:143], v[60:63], 0
	v_mfma_f32_16x16x32_bf16 v[28:31], v[144:147], v[60:63], 0
	v_mfma_f32_16x16x32_bf16 v[16:19], v[148:151], v[72:75], v[16:19]
	v_mfma_f32_16x16x32_bf16 v[20:23], v[152:155], v[72:75], v[20:23]
	v_mfma_f32_16x16x32_bf16 v[24:27], v[116:119], v[72:75], v[24:27]
	v_mfma_f32_16x16x32_bf16 v[28:31], v[120:123], v[72:75], v[28:31]
	v_mfma_f32_16x16x32_bf16 v[32:35], v[132:135], v[76:79], 0
	v_mfma_f32_16x16x32_bf16 v[36:39], v[136:139], v[76:79], 0
	v_mfma_f32_16x16x32_bf16 v[40:43], v[140:143], v[76:79], 0
	v_mfma_f32_16x16x32_bf16 v[44:47], v[144:147], v[76:79], 0
	v_mfma_f32_16x16x32_bf16 v[32:35], v[148:151], v[80:83], v[32:35]
	v_mfma_f32_16x16x32_bf16 v[36:39], v[152:155], v[80:83], v[36:39]
	v_mfma_f32_16x16x32_bf16 v[40:43], v[116:119], v[80:83], v[40:43]
	v_mfma_f32_16x16x32_bf16 v[44:47], v[120:123], v[80:83], v[44:47]
	s_nop 3
	ds_read_b64 v[132:133], v126 offset:8192
	ds_read_b64 v[134:135], v127 offset:8192
	ds_read_b64 v[148:149], v128 offset:8192
	ds_read_b64 v[150:151], v129 offset:8192
	ds_read_b64 v[136:137], v126 offset:10240
	ds_read_b64 v[138:139], v127 offset:10240
	ds_read_b64 v[152:153], v128 offset:10240
	ds_read_b64 v[154:155], v129 offset:10240
	ds_read_b64 v[140:141], v126 offset:12288
	ds_read_b64 v[142:143], v127 offset:12288
	ds_read_b64 v[116:117], v128 offset:12288
	ds_read_b64 v[118:119], v129 offset:12288
	ds_read_b64 v[144:145], v126 offset:14336
	ds_read_b64 v[146:147], v127 offset:14336
	ds_read_b64 v[120:121], v128 offset:14336
	ds_read_b64 v[122:123], v129 offset:14336
	v_exp_f32_e32 v16, v16
	v_exp_f32_e32 v17, v17
	v_exp_f32_e32 v18, v18
	v_exp_f32_e32 v19, v19
	v_exp_f32_e32 v20, v20
	v_exp_f32_e32 v21, v21
	v_exp_f32_e32 v22, v22
	v_exp_f32_e32 v23, v23
	v_exp_f32_e32 v24, v24
	v_exp_f32_e32 v25, v25
	v_exp_f32_e32 v26, v26
	v_exp_f32_e32 v27, v27
	v_exp_f32_e32 v28, v28
	v_exp_f32_e32 v29, v29
	v_exp_f32_e32 v30, v30
	v_exp_f32_e32 v31, v31
	v_pk_add_f32 v[124:125], v[16:17], v[18:19]
	v_pk_add_f32 v[126:127], v[20:21], v[22:23]
	v_pk_add_f32 v[128:129], v[24:25], v[26:27]
	v_pk_add_f32 v[252:253], v[28:29], v[30:31]
	v_pk_add_f32 v[124:125], v[124:125], v[126:127]
	v_pk_add_f32 v[128:129], v[128:129], v[252:253]
	v_pk_add_f32 v[124:125], v[124:125], v[128:129]
	v_add_f32_e32 v124, v124, v125
	s_cmp_eq_u64 s[98:99], -1
	s_cbranch_scc1 .Lsf_b0_a
	v_cndmask_b32_e64 v251, 0, -1, s[98:99]
	v_and_b32_e32 v124, v124, v251
.Lsf_b0_a:
	v_add_f32_e32 v172, v172, v124
	v_cvt_pk_bf16_f32 v16, v16, v17
	v_cvt_pk_bf16_f32 v17, v18, v19
	v_cvt_pk_bf16_f32 v18, v20, v21
	v_cvt_pk_bf16_f32 v19, v22, v23
	v_cvt_pk_bf16_f32 v20, v24, v25
	v_cvt_pk_bf16_f32 v21, v26, v27
	v_cvt_pk_bf16_f32 v22, v28, v29
	v_cvt_pk_bf16_f32 v23, v30, v31
	s_cmp_eq_u64 s[98:99], -1
	s_cbranch_scc1 .Lsf_b0_b
	v_and_b32_e32 v16, v16, v251
	v_and_b32_e32 v17, v17, v251
	v_and_b32_e32 v18, v18, v251
	v_and_b32_e32 v19, v19, v251
	v_and_b32_e32 v20, v20, v251
	v_and_b32_e32 v21, v21, v251
	v_and_b32_e32 v22, v22, v251
	v_and_b32_e32 v23, v23, v251
.Lsf_b0_b:
	s_waitcnt lgkmcnt(0)
	s_nop 0
	v_exp_f32_e32 v32, v32
	v_exp_f32_e32 v33, v33
	v_mfma_f32_16x16x32_bf16 v[112:115], v[132:135], v[16:19], v[112:115]
	v_exp_f32_e32 v34, v34
	v_exp_f32_e32 v35, v35
	v_mfma_f32_16x16x32_bf16 v[108:111], v[136:139], v[16:19], v[108:111]
	v_exp_f32_e32 v36, v36
	v_exp_f32_e32 v37, v37
	v_mfma_f32_16x16x32_bf16 v[104:107], v[140:143], v[16:19], v[104:107]
	v_exp_f32_e32 v38, v38
	v_exp_f32_e32 v39, v39
	v_mfma_f32_16x16x32_bf16 v[100:103], v[144:147], v[16:19], v[100:103]
	v_exp_f32_e32 v40, v40
	v_exp_f32_e32 v41, v41
	v_mfma_f32_16x16x32_bf16 v[112:115], v[148:151], v[20:23], v[112:115]
	v_exp_f32_e32 v42, v42
	v_exp_f32_e32 v43, v43
	v_mfma_f32_16x16x32_bf16 v[108:111], v[152:155], v[20:23], v[108:111]
	v_exp_f32_e32 v44, v44
	v_exp_f32_e32 v45, v45
	v_mfma_f32_16x16x32_bf16 v[104:107], v[116:119], v[20:23], v[104:107]
	v_exp_f32_e32 v46, v46
	v_exp_f32_e32 v47, v47
	v_mfma_f32_16x16x32_bf16 v[100:103], v[120:123], v[20:23], v[100:103]
	v_pk_add_f32 v[124:125], v[32:33], v[34:35]
	v_pk_add_f32 v[126:127], v[36:37], v[38:39]
	v_pk_add_f32 v[128:129], v[40:41], v[42:43]
	v_pk_add_f32 v[252:253], v[44:45], v[46:47]
	v_pk_add_f32 v[124:125], v[124:125], v[126:127]
	v_pk_add_f32 v[128:129], v[128:129], v[252:253]
	v_pk_add_f32 v[124:125], v[124:125], v[128:129]
	v_add_f32_e32 v124, v124, v125
	s_cmp_eq_u64 s[100:101], -1
	s_cbranch_scc1 .Lsf_b1_a
	v_cndmask_b32_e64 v251, 0, -1, s[100:101]
	v_and_b32_e32 v124, v124, v251
.Lsf_b1_a:
	v_add_f32_e32 v173, v173, v124
	v_cvt_pk_bf16_f32 v32, v32, v33
	v_cvt_pk_bf16_f32 v33, v34, v35
	v_cvt_pk_bf16_f32 v34, v36, v37
	v_cvt_pk_bf16_f32 v35, v38, v39
	v_cvt_pk_bf16_f32 v36, v40, v41
	v_cvt_pk_bf16_f32 v37, v42, v43
	v_cvt_pk_bf16_f32 v38, v44, v45
	v_cvt_pk_bf16_f32 v39, v46, v47
	s_cmp_eq_u64 s[100:101], -1
	s_cbranch_scc1 .Lsf_b1_b
	v_and_b32_e32 v32, v32, v251
	v_and_b32_e32 v33, v33, v251
	v_and_b32_e32 v34, v34, v251
	v_and_b32_e32 v35, v35, v251
	v_and_b32_e32 v36, v36, v251
	v_and_b32_e32 v37, v37, v251
	v_and_b32_e32 v38, v38, v251
	v_and_b32_e32 v39, v39, v251

; template <int MODE> __device__ __forceinline__ void tile_softmax(f32x4 (&S)[4], bool rowv, int kfirst, int klo, unsigned kspan, float& l) {
;     ...
;         for (int j = 0; j < 4; ++j) { float e = __builtin_amdgcn_exp2f(S[st][j]);
;             if (MODE == 1) e = rowv ? e : 0.f;
;             if (MODE == 2) e = ((unsigned)(kfirst + st * 16 + j - klo) <= kspan) ? e : 0.f;
;             S[st][j] = e; ps += e; }
;     l += ps;
.Lsf_only0:
	v_mfma_f32_16x16x32_bf16 v[16:19], v[132:135], v[60:63], 0
	v_mfma_f32_16x16x32_bf16 v[20:23], v[136:139], v[60:63], 0
	v_mfma_f32_16x16x32_bf16 v[24:27], v[140:143], v[60:63], 0
	v_mfma_f32_16x16x32_bf16 v[28:31], v[144:147], v[60:63], 0
	v_mfma_f32_16x16x32_bf16 v[16:19], v[148:151], v[72:75], v[16:19]
	v_mfma_f32_16x16x32_bf16 v[20:23], v[152:155], v[72:75], v[20:23]
	v_mfma_f32_16x16x32_bf16 v[24:27], v[116:119], v[72:75], v[24:27]
	v_mfma_f32_16x16x32_bf16 v[28:31], v[120:123], v[72:75], v[28:31]
	s_nop 3
	ds_read_b64 v[132:133], v126 offset:8192
	ds_read_b64 v[134:135], v127 offset:8192
	ds_read_b64 v[148:149], v128 offset:8192
	ds_read_b64 v[150:151], v129 offset:8192
	ds_read_b64 v[136:137], v126 offset:10240
	ds_read_b64 v[138:139], v127 offset:10240
	ds_read_b64 v[152:153], v128 offset:10240
	ds_read_b64 v[154:155], v129 offset:10240
	ds_read_b64 v[140:141], v126 offset:12288
	ds_read_b64 v[142:143], v127 offset:12288
	ds_read_b64 v[116:117], v128 offset:12288
	ds_read_b64 v[118:119], v129 offset:12288
	ds_read_b64 v[144:145], v126 offset:14336
	ds_read_b64 v[146:147], v127 offset:14336
	ds_read_b64 v[120:121], v128 offset:14336
	ds_read_b64 v[122:123], v129 offset:14336
	s_nop 7
	v_exp_f32_e32 v16, v16
	v_exp_f32_e32 v17, v17
	v_exp_f32_e32 v18, v18
	v_exp_f32_e32 v19, v19
	v_exp_f32_e32 v20, v20
	v_exp_f32_e32 v21, v21
	v_exp_f32_e32 v22, v22
	v_exp_f32_e32 v23, v23
	v_exp_f32_e32 v24, v24
	v_exp_f32_e32 v25, v25
	v_exp_f32_e32 v26, v26
	v_exp_f32_e32 v27, v27
	v_exp_f32_e32 v28, v28
	v_exp_f32_e32 v29, v29
	v_exp_f32_e32 v30, v30
	v_exp_f32_e32 v31, v31
	v_pk_add_f32 v[124:125], v[16:17], v[18:19]
	v_pk_add_f32 v[126:127], v[20:21], v[22:23]
	v_pk_add_f32 v[128:129], v[24:25], v[26:27]
	v_pk_add_f32 v[252:253], v[28:29], v[30:31]
	v_pk_add_f32 v[124:125], v[124:125], v[126:127]
	v_pk_add_f32 v[128:129], v[128:129], v[252:253]
	v_pk_add_f32 v[124:125], v[124:125], v[128:129]
	v_add_f32_e32 v124, v124, v125
	s_cmp_eq_u64 s[98:99], -1
	s_cbranch_scc1 .Lsf_o0_a
	v_cndmask_b32_e64 v251, 0, -1, s[98:99]
	v_and_b32_e32 v124, v124, v251

; template <int MODE> __device__ __forceinline__ void tile_softmax(f32x4 (&S)[4], bool rowv, int kfirst, int klo, unsigned kspan, float& l) {
;     ...
;         for (int j = 0; j < 4; ++j) { float e = __builtin_amdgcn_exp2f(S[st][j]);
;             if (MODE == 1) e = rowv ? e : 0.f;
;             if (MODE == 2) e = ((unsigned)(kfirst + st * 16 + j - klo) <= kspan) ? e : 0.f;
;             S[st][j] = e; ps += e; }
;     l += ps;
.Lsf_only1:
	v_mfma_f32_16x16x32_bf16 v[32:35], v[132:135], v[76:79], 0
	v_mfma_f32_16x16x32_bf16 v[36:39], v[136:139], v[76:79], 0
	v_mfma_f32_16x16x32_bf16 v[40:43], v[140:143], v[76:79], 0
	v_mfma_f32_16x16x32_bf16 v[44:47], v[144:147], v[76:79], 0
	v_mfma_f32_16x16x32_bf16 v[32:35], v[148:151], v[80:83], v[32:35]
	v_mfma_f32_16x16x32_bf16 v[36:39], v[152:155], v[80:83], v[36:39]
	v_mfma_f32_16x16x32_bf16 v[40:43], v[116:119], v[80:83], v[40:43]
	v_mfma_f32_16x16x32_bf16 v[44:47], v[120:123], v[80:83], v[44:47]
	s_nop 3
	ds_read_b64 v[132:133], v126 offset:8192
	ds_read_b64 v[134:135], v127 offset:8192
	ds_read_b64 v[148:149], v128 offset:8192
	ds_read_b64 v[150:151], v129 offset:8192
	ds_read_b64 v[136:137], v126 offset:10240
	ds_read_b64 v[138:139], v127 offset:10240
	ds_read_b64 v[152:153], v128 offset:10240
	ds_read_b64 v[154:155], v129 offset:10240
	ds_read_b64 v[140:141], v126 offset:12288
	ds_read_b64 v[142:143], v127 offset:12288
	ds_read_b64 v[116:117], v128 offset:12288
	ds_read_b64 v[118:119], v129 offset:12288
	ds_read_b64 v[144:145], v126 offset:14336
	ds_read_b64 v[146:147], v127 offset:14336
	ds_read_b64 v[120:121], v128 offset:14336
	ds_read_b64 v[122:123], v129 offset:14336
	s_nop 7
	v_exp_f32_e32 v32, v32
	v_exp_f32_e32 v33, v33
	v_exp_f32_e32 v34, v34
	v_exp_f32_e32 v35, v35
	v_exp_f32_e32 v36, v36
	v_exp_f32_e32 v37, v37
	v_exp_f32_e32 v38, v38
	v_exp_f32_e32 v39, v39
	v_exp_f32_e32 v40, v40
	v_exp_f32_e32 v41, v41
	v_exp_f32_e32 v42, v42
	v_exp_f32_e32 v43, v43
	v_exp_f32_e32 v44, v44
	v_exp_f32_e32 v45, v45
	v_exp_f32_e32 v46, v46
	v_exp_f32_e32 v47, v47
	v_pk_add_f32 v[124:125], v[32:33], v[34:35]
	v_pk_add_f32 v[126:127], v[36:37], v[38:39]
	v_pk_add_f32 v[128:129], v[40:41], v[42:43]
	v_pk_add_f32 v[252:253], v[44:45], v[46:47]
	v_pk_add_f32 v[124:125], v[124:125], v[126:127]
	v_pk_add_f32 v[128:129], v[128:129], v[252:253]
	v_pk_add_f32 v[124:125], v[124:125], v[128:129]
	v_add_f32_e32 v124, v124, v125
	s_cmp_eq_u64 s[100:101], -1
	s_cbranch_scc1 .Lsf_o1_a
	v_cndmask_b32_e64 v251, 0, -1, s[100:101]
	v_and_b32_e32 v124, v124, v251
